# panel-counter poll loops sleep 1 instead of 2 between polls (otherwise v093)
# baseline (speedup 1.0000x reference)
; #define lane lane_id()
; __global__ void __launch_bounds__(NWAVES * 64, 2) fwd_kernel(Args a) {
;     ...
;     if (IN(1)) for (int rep = 0; rep < NREP(1); ++rep) {
;         pg8::Gemm g{HN0, WT1, NTOK, 3 * GW, DM}; pg8::ConvOrder S; S.init(NTOK, 3 * GW, G, bx);
;         S.w2 = a_w_out; S.w3 = b_w_in; S.w4 = b_w_out; S.g1 = norm_g + DM; S.t2 = WT2; S.t3 = WT3; S.t4 = WT4; S.gw = gw; S.ngw = NGW; S.trigger = (G == 256) ? CONV_TRIGGER : 0; S.ln = lane; S.sw = lds + 131072 + wave * 2048; S.n_done = 0;
;         pg8::EpiGmlpIn E{U, V, VSS};
;         pg8::gemm_phase<pg8::EpiGmlpIn, pg8::ConvOrder, GEMM_ALIGN, GEMM_SP2>(lds, g, S, E, wave);
.Lp1_poll_c0:
	global_load_dword v237, v236, s[68:69] sc1
	s_waitcnt vmcnt(0)
	v_readfirstlane_b32 s101, v237
	s_cmpk_ge_u32 s101, 0x100
	s_cbranch_scc1 .Lp1_got_c0
	s_add_i32 s100, s100, 1
	s_cmp_lt_u32 s100, 0x10000
	s_cbranch_scc0 .Lp1_got_c0
	s_sleep 1
	s_branch .Lp1_poll_c0

; __global__ void __launch_bounds__(NWAVES * 64, 2) fwd_kernel(Args a) {
;     ...
;     if (IN(3)) for (int rep = 0; rep < NREP(3); ++rep) {
;         pg8::Gemm g{Y, WT2, NTOK, DM, GW}; pg8::StaticOrder S; S.init(NTOK, DM, G, bx);
;         pg8::EpiRes1 E{HN0, IRS0, H1B, HSS1};
;         pg8::gemm_phase<pg8::EpiRes1, pg8::StaticOrder, GEMM_ALIGN, GEMM_SP2>(lds, g, S, E, wave);
.Lp3_poll:
	global_load_dword v237, v236, s[98:99] sc1
	s_waitcnt vmcnt(0)
	v_readfirstlane_b32 s101, v237
	s_cmpk_ge_u32 s101, 0x100
	s_cbranch_scc1 .Lp3_meet
	s_add_i32 s100, s100, 1
	s_cmp_lt_u32 s100, 0x10000
	s_cbranch_scc0 .Lp3_meet
	s_sleep 1
	s_branch .Lp3_poll

; __global__ void __launch_bounds__(NWAVES * 64, 2) fwd_kernel(Args a) {
;     ...
;     if (IN(4)) for (int rep = 0; rep < NREP(4); ++rep) {
;         pg8::Gemm g{H1B, WT3, NTOK, 4 * DM, DM}; pg8::StaticOrder S; S.init(NTOK, 4 * DM, G, bx);
;         pg8::EpiSbIn E{Qb, (size_t)(WS_K - WS_Q) / 2, HSS1};
;         pg8::gemm_phase<pg8::EpiSbIn, pg8::StaticOrder, GEMM_ALIGN, GEMM_SP2>(lds, g, S, E, wave);
.Lp4_poll:
	global_load_dword v237, v236, s[98:99] sc1
	s_waitcnt vmcnt(0)
	v_readfirstlane_b32 s101, v237
	s_cmpk_ge_u32 s101, 0x40
	s_cbranch_scc1 .Lp4_meet
	s_add_i32 s100, s100, 1
	s_cmp_lt_u32 s100, 0x10000
	s_cbranch_scc0 .Lp4_meet
	s_sleep 1
	s_branch .Lp4_poll

; __global__ void __launch_bounds__(NWAVES * 64, 2) fwd_kernel(Args a) {
;     ...
;     if (IN(6)) for (int rep = 0; rep < NREP(6); ++rep) {
;         pg8::Gemm g{OG, WT4, NTOK, DM, DM}; pg8::StaticOrder S; S.init(NTOK, DM, G, bx);
;         pg8::EpiFinal E{H1B, final_g, a.out, HSS2, CNT, G == 256};
;         pg8::gemm_phase<pg8::EpiFinal, pg8::StaticOrder, GEMM_ALIGN, GEMM_SP2>(lds, g, S, E, wave);
.Lp6_poll:
	global_load_dword v237, v236, s[98:99] sc1
	s_waitcnt vmcnt(0)
	v_readfirstlane_b32 s101, v237
	s_cmpk_ge_u32 s101, 0x80
	s_cbranch_scc1 .Lp6_meet
	s_add_i32 s100, s100, 1
	s_cmp_lt_u32 s100, 0x10000
	s_cbranch_scc0 .Lp6_meet
	s_sleep 1
	s_branch .Lp6_poll
